# attention: scalar probe of both queue counters per k, skip exhausted queues instead of a returning atomic each
# baseline (speedup 1.0000x reference)
; __device__ __forceinline__ void phase_attn(const Ctx& C, const float* relb  , int layer) {
;     ...
;       for (int k = 0; k < 8; ++k) { const int x = (((int)blockIdx.x & 7) + k * (1 + 2 * (((int)blockIdx.x >> 3) & 3))) & 7;
;           unsigned* qb_ = (unsigned*)(ws_ + WS_BAR) + WQ_WORD + 64 * (8 * layer + x);
;           unsigned* qa_ = (unsigned*)(ws_ + WS_BAR) + WQ_WORD + 64 * (16 + 8 * layer + x);
;           for (;;) {
;               unsigned idx = 0;
;               if (lane == 0) idx = __hip_atomic_fetch_add(qb_, 1u, __ATOMIC_RELAXED, __HIP_MEMORY_SCOPE_AGENT);
;               idx = (unsigned)__builtin_amdgcn_readfirstlane((int)idx);
;               if (idx >= (unsigned)per_q) break;
.LBB0_262:
	v_readlane_b32 s2, v255, 7
	s_mul_i32 s2, s19, s2
	v_readlane_b32 s3, v254, 0
	s_add_i32 s2, s2, s3
	s_mov_b32 s1, s78
	s_and_b32 s78, s2, 7
	s_lshl_b32 s2, s78, 6
	v_readlane_b32 s3, v255, 47
	s_or_b32 s10, s2, s3
	s_lshl_b64 s[2:3], s[10:11], 2
	v_readlane_b32 s10, v255, 43
	s_add_u32 s20, s10, s2
	v_readlane_b32 s2, v255, 44
	s_addc_u32 s21, s2, s3
	s_lshl_b32 s2, s78, 12
	s_mul_i32 s3, s78, 0x1800000
	s_add_u32 s12, s14, s3
	s_addc_u32 s13, s15, 0
	v_lshl_add_u64 v[134:135], v[116:117], 1, s[12:13]
	s_mov_b64 s[12:13], 0x1400
	s_lshl_b32 s10, s78, 14
	v_lshl_add_u64 v[98:99], v[134:135], 0, s[12:13]
	v_or_b32_e32 v136, s2, v114
	v_lshl_add_u64 v[100:101], v[130:131], 0, s[10:11]
	s_load_dword s98, s[20:21], 0x0 glc
	s_load_dword s99, s[20:21], 0x1000 glc
	s_waitcnt lgkmcnt(0)
	s_cmpk_gt_u32 s98, 0x3ff
	s_cbranch_scc1 .LBB0_299
	s_branch .LBB0_265

; __device__ __forceinline__ void phase_attn(const Ctx& C, const float* relb  , int layer) {
;     ...
;           for (;;) {
;               unsigned idx = 0;
;               if (lane == 0) idx = __hip_atomic_fetch_add(qa_, 1u, __ATOMIC_RELAXED, __HIP_MEMORY_SCOPE_AGENT);
;               idx = (unsigned)__builtin_amdgcn_readfirstlane((int)idx);
;               if (idx >= (unsigned)per_q) break;
.LBB0_299:
	s_add_u32 s20, s20, 0x1000
	s_addc_u32 s21, s21, 0
	s_lshl_b32 s10, s2, 2
	v_lshl_add_u64 v[138:139], v[134:135], 0, s[90:91]
	v_lshl_add_u64 v[140:141], v[132:133], 0, s[10:11]
	s_mov_b32 s78, s1
	s_cmpk_gt_u32 s99, 0x3ff
	s_cbranch_scc1 .LBB0_261
	s_branch .LBB0_302
